# prepD rows: the serialized pairs of 2-byte loads for the input-rank sum of squares issued together, one wait (same arithmetic)
# speedup vs baseline: 1.3281x; 1.0193x over previous
; DI float bf2f(bf16_t b) { return __uint_as_float(((unsigned)b) << 16); }
; NI void prepD_row(const P& p, int l, int t0) {
;     ...
;   for (int task = hw; task < 12; task += 8) {
;     const int hd = task & 3;
;     const bool isq = task < 4;
;     float ssi[RBD];
;     if (isq) {
; #pragma unroll
;       for (int rr = 0; rr < RBD; ++rr) { float a = 0.f;
; #pragma unroll
;         for (int j = 0; j < 12; ++j) { const float v = bf2f(U[(size_t)(t0 + rr) * INP + O_DCQ + ln + 32 * j]); a += v * v; }
;         ssi[rr] = a; }
;     } else {
; #pragma unroll
;       for (int rr = 0; rr < RBD; ++rr) { float a = 0.f;
; #pragma unroll
;         for (int j = 0; j < 8; ++j) { const float v = bf2f(U[(size_t)(t0 + rr) * INP + O_DCKV + ln + 32 * j]); a += v * v; }
;         ssi[rr] = a; }
;     }
.LBB0_183:
	v_cmp_gt_i32_e64 s[22:23], 4, v106
	v_cmp_lt_i32_e64 s[24:25], 3, v106
	s_and_saveexec_b64 s[18:19], s[24:25]
	s_xor_b64 s[18:19], exec, s[18:19]
	s_cbranch_execz .LBB0_185
	global_load_ushort v176, v[2:3], off
	global_load_ushort v177, v[2:3], off offset:64
	global_load_ushort v178, v[2:3], off offset:128
	global_load_ushort v179, v[2:3], off offset:192
	global_load_ushort v180, v[2:3], off offset:256
	global_load_ushort v181, v[2:3], off offset:320
	global_load_ushort v182, v[2:3], off offset:384
	global_load_ushort v183, v[2:3], off offset:448
	global_load_ushort v184, v[4:5], off offset:64
	global_load_ushort v185, v[4:5], off
	global_load_ushort v186, v[4:5], off offset:128
	global_load_ushort v190, v[4:5], off offset:192
	global_load_ushort v191, v[4:5], off offset:256
	s_waitcnt vmcnt(0)
	v_lshlrev_b32_e32 v88, 16, v176
	v_lshlrev_b32_e32 v89, 16, v177
	v_mul_f32_e32 v90, v89, v89
	v_pk_fma_f32 v[88:89], v[88:89], v[88:89], v[90:91] op_sel_hi:[1,1,0]
	v_lshlrev_b32_e32 v90, 16, v178
	v_lshlrev_b32_e32 v91, 16, v179
	v_pk_fma_f32 v[88:89], v[90:91], v[90:91], v[88:89]
	v_mul_f32_e32 v90, v91, v91
	v_pk_add_f32 v[88:89], v[88:89], v[90:91] op_sel_hi:[1,0]
	v_lshlrev_b32_e32 v90, 16, v180
	v_lshlrev_b32_e32 v91, 16, v181
	v_pk_fma_f32 v[88:89], v[90:91], v[90:91], v[88:89]
	v_mul_f32_e32 v90, v91, v91
	v_pk_add_f32 v[88:89], v[88:89], v[90:91] op_sel_hi:[1,0]
	v_lshlrev_b32_e32 v90, 16, v182
	v_lshlrev_b32_e32 v91, 16, v183
	v_pk_fma_f32 v[88:89], v[90:91], v[90:91], v[88:89]
	v_mul_f32_e32 v90, v91, v91
	v_pk_add_f32 v[88:89], v[88:89], v[90:91] op_sel_hi:[1,0]
	v_lshlrev_b32_e32 v90, 16, v185
	v_lshlrev_b32_e32 v91, 16, v186
	v_lshlrev_b32_e32 v89, 16, v184
	v_pk_mul_f32 v[90:91], v[90:91], v[90:91]
	s_nop 0
	v_fma_f32 v89, v89, v89, v90
	v_add_f32_e32 v89, v89, v91
	v_lshlrev_b32_e32 v90, 16, v190
	v_lshlrev_b32_e32 v91, 16, v191
	v_pk_mul_f32 v[90:91], v[90:91], v[90:91]
	s_nop 0
	v_add_f32_e32 v89, v89, v90
	v_add_f32_e32 v112, v89, v91
.LBB0_185:
	s_or_saveexec_b64 s[18:19], s[18:19]
	v_mov_b64_e32 v[90:91], v[6:7]
	s_waitcnt vmcnt(0)
	v_mov_b64_e32 v[92:93], v[8:9]
	v_mov_b64_e32 v[94:95], v[10:11]
	s_xor_b64 exec, exec, s[18:19]
	s_cbranch_execz .LBB0_187
	global_load_ushort v176, v[12:13], off
	global_load_ushort v177, v[12:13], off offset:64
	global_load_ushort v178, v[12:13], off offset:128
	global_load_ushort v179, v[12:13], off offset:192
	global_load_ushort v180, v[12:13], off offset:256
	global_load_ushort v181, v[12:13], off offset:320
	global_load_ushort v182, v[12:13], off offset:384
	global_load_ushort v183, v[12:13], off offset:448
	global_load_ushort v184, v[12:13], off offset:512
	global_load_ushort v185, v[12:13], off offset:576
	global_load_ushort v186, v[12:13], off offset:640
	global_load_ushort v190, v[12:13], off offset:704
	global_load_ushort v191, v[14:15], off offset:64
	global_load_ushort v192, v[14:15], off
	global_load_ushort v193, v[14:15], off offset:128
	global_load_ushort v194, v[14:15], off offset:192
	global_load_ushort v195, v[14:15], off offset:256
	global_load_ushort v196, v[14:15], off offset:320
	global_load_ushort v197, v[14:15], off offset:384
	global_load_ushort v198, v[14:15], off offset:448
	global_load_ushort v199, v[14:15], off offset:512
	s_waitcnt vmcnt(0)
	v_mov_b64_e32 v[92:93], v[18:19]
	v_mov_b64_e32 v[94:95], v[20:21]
	v_lshlrev_b32_e32 v88, 16, v176
	v_lshlrev_b32_e32 v89, 16, v177
	v_mul_f32_e32 v90, v89, v89
	v_pk_fma_f32 v[88:89], v[88:89], v[88:89], v[90:91] op_sel_hi:[1,1,0]
	v_lshlrev_b32_e32 v90, 16, v178
	v_lshlrev_b32_e32 v91, 16, v179
	v_pk_fma_f32 v[88:89], v[90:91], v[90:91], v[88:89]
	v_mul_f32_e32 v90, v91, v91
	v_pk_add_f32 v[88:89], v[88:89], v[90:91] op_sel_hi:[1,0]
	v_lshlrev_b32_e32 v90, 16, v180
	v_lshlrev_b32_e32 v91, 16, v181
	v_pk_fma_f32 v[88:89], v[90:91], v[90:91], v[88:89]
	v_mul_f32_e32 v90, v91, v91
	v_pk_add_f32 v[88:89], v[88:89], v[90:91] op_sel_hi:[1,0]
	v_lshlrev_b32_e32 v90, 16, v182
	v_lshlrev_b32_e32 v91, 16, v183
	v_pk_fma_f32 v[88:89], v[90:91], v[90:91], v[88:89]
	v_mul_f32_e32 v90, v91, v91
	v_pk_add_f32 v[88:89], v[88:89], v[90:91] op_sel_hi:[1,0]
	v_lshlrev_b32_e32 v90, 16, v184
	v_lshlrev_b32_e32 v91, 16, v185
	v_pk_fma_f32 v[88:89], v[90:91], v[90:91], v[88:89]
	v_mul_f32_e32 v90, v91, v91
	v_pk_add_f32 v[88:89], v[88:89], v[90:91] op_sel_hi:[1,0]
	v_lshlrev_b32_e32 v90, 16, v186
	v_lshlrev_b32_e32 v91, 16, v190
	v_pk_fma_f32 v[88:89], v[90:91], v[90:91], v[88:89]
	v_mul_f32_e32 v90, v91, v91
	v_pk_add_f32 v[88:89], v[88:89], v[90:91] op_sel_hi:[1,0]
	v_lshlrev_b32_e32 v90, 16, v192
	v_lshlrev_b32_e32 v91, 16, v193
	v_lshlrev_b32_e32 v89, 16, v191
	v_pk_mul_f32 v[90:91], v[90:91], v[90:91]
	s_nop 0
	v_fma_f32 v89, v89, v89, v90
	v_add_f32_e32 v89, v89, v91
	v_lshlrev_b32_e32 v90, 16, v194
	v_lshlrev_b32_e32 v91, 16, v195
	v_pk_mul_f32 v[90:91], v[90:91], v[90:91]
	s_nop 0
	v_add_f32_e32 v89, v89, v90
	v_add_f32_e32 v89, v89, v91
	v_lshlrev_b32_e32 v90, 16, v196
	v_lshlrev_b32_e32 v91, 16, v197
	v_pk_mul_f32 v[90:91], v[90:91], v[90:91]
	s_nop 0
	v_add_f32_e32 v89, v89, v90
	v_add_f32_e32 v89, v89, v91
	v_lshlrev_b32_e32 v90, 16, v198
	v_lshlrev_b32_e32 v91, 16, v199
	v_pk_mul_f32 v[90:91], v[90:91], v[90:91]
	s_nop 0
	v_add_f32_e32 v89, v89, v90
	v_add_f32_e32 v112, v89, v91
	v_mov_b64_e32 v[90:91], v[16:17]
